# P3 LoRA GEMM epilogue: w0/a0 parameter vectors loaded once per tile instead of per row group (on top of the P5 change)
# speedup vs baseline: 1.0042x; 1.0042x over previous
; __device__ __forceinline__ unsigned cvt_pk_bf16(float lo, float hi) { unsigned r; asm volatile("v_cvt_pk_bf16_f32 %0, %1, %2" : "=v"(r) : "v"(lo), "v"(hi)); return r; }
; __device__ __forceinline__ float sigmoidf_(float x) { return __builtin_amdgcn_rcpf(1.0f + __expf(-x)); }
;     __device__ __forceinline__ void operator()(f32x4 (&acc)[2][2][4][2], const Unit& u, int wr, int wc, int fr, int fq) const {
;     ...
;                 bf16_t* rowp = O + (size_t)(row0 + ai * HALF + m * 16) * ldc + col0;
; #pragma unroll
;                 for (int bj = 0; bj < 2; ++bj) {
;                     f32x4 v0 = acc[ai][bj][m][0], v1 = acc[ai][bj][m][1];
;                     f(v0, v1, u.pn, col0 + bj * HALF);
;                     u32x4 w; w.x = cvt_pk_bf16(v0[0], v0[1]); w.y = cvt_pk_bf16(v0[2], v0[3]); w.z = cvt_pk_bf16(v1[0], v1[1]); w.w = cvt_pk_bf16(v1[2], v1[3]);
;                     *(u32x4*)(rowp + bj * HALF) = w;
;                 }
;     __device__ __forceinline__ void operator()(f32x4& a, f32x4& b, int pn, int col) const {
;         if (pn < 8) {
;             const float* pp = (pn < 4) ? (w0 + col) : (a0 + col - 1024);
;             const float sc = (pn < 4) ? -0.6065306597126334f : 1.0f;
;             const f32x4 p0 = *(const f32x4*)pp, p1 = *(const f32x4*)(pp + 4);
; #pragma unroll
;             for (int j = 0; j < 4; ++j) { a[j] = sc * sigmoidf_(a[j] + p0[j]); b[j] = sc * sigmoidf_(b[j] + p1[j]); }
;         }
.LBB0_497:
	v_mov_b32_e32 v143, v210
	s_cmp_lt_i32 s80, 8
	v_lshrrev_b32_e32 v142, 1, v143
	v_and_b32_e32 v142, 0x78, v142
	v_lshl_or_b32 v148, s80, 8, v142
	v_ashrrev_i32_e32 v149, 31, v148
	s_cselect_b64 s[86:87], -1, 0
	s_cmp_lt_i32 s80, 4
	s_cselect_b64 s[40:41], -1, 0
	v_lshlrev_b64 v[144:145], 2, v[148:149]
	s_cmp_gt_i32 s80, 7
	v_cndmask_b32_e64 v142, 1.0, v218, s[40:41]
	v_lshl_add_u64 v[146:147], s[36:37], 0, v[144:145]
	v_lshl_add_u64 v[144:145], s[48:49], 0, v[144:145]
	s_cbranch_scc1 .LBB0_499
	s_movk_i32 s12, 0xf000
	s_mov_b32 s13, -1
	v_lshl_add_u64 v[150:151], v[144:145], 0, s[12:13]
	v_cndmask_b32_e64 v151, v151, v147, s[40:41]
	v_cndmask_b32_e64 v150, v150, v146, s[40:41]
	global_load_dwordx4 v[186:189], v[150:151], off
	global_load_dwordx4 v[190:193], v[150:151], off offset:16
	global_load_dwordx4 v[194:197], v[150:151], off offset:512
	global_load_dwordx4 v[198:201], v[150:151], off offset:528
	s_waitcnt vmcnt(0)
	v_mov_b32_e32 v154, v186
	v_mov_b32_e32 v155, v187
	v_mov_b32_e32 v156, v188
	v_mov_b32_e32 v157, v189
	v_mov_b32_e32 v158, v190
	v_mov_b32_e32 v159, v191
	v_mov_b32_e32 v160, v192
	v_mov_b32_e32 v161, v193
	v_add_f32_e32 v126, v126, v154
	v_add_f32_e32 v122, v122, v158
	v_add_f32_e32 v127, v127, v155
	v_add_f32_e32 v123, v123, v159
	v_add_f32_e32 v128, v128, v156
	v_add_f32_e32 v124, v124, v160
	v_add_f32_e32 v129, v129, v157
	v_add_f32_e32 v125, v125, v161
	v_mul_f32_e32 v126, 0xbfb8aa3b, v126
	v_mul_f32_e32 v122, 0xbfb8aa3b, v122
	v_mul_f32_e32 v127, 0xbfb8aa3b, v127
	v_mul_f32_e32 v123, 0xbfb8aa3b, v123
	v_mul_f32_e32 v128, 0xbfb8aa3b, v128
	v_mul_f32_e32 v124, 0xbfb8aa3b, v124
	v_mul_f32_e32 v129, 0xbfb8aa3b, v129
	v_mul_f32_e32 v125, 0xbfb8aa3b, v125
	v_exp_f32_e32 v126, v126
	v_exp_f32_e32 v122, v122
	v_exp_f32_e32 v127, v127
	v_exp_f32_e32 v123, v123
	v_exp_f32_e32 v128, v128
	v_exp_f32_e32 v124, v124
	v_exp_f32_e32 v129, v129
	v_exp_f32_e32 v125, v125
	v_add_f32_e32 v126, 1.0, v126
	v_add_f32_e32 v150, 1.0, v122
	v_add_f32_e32 v127, 1.0, v127
	v_add_f32_e32 v151, 1.0, v123
	v_add_f32_e32 v128, 1.0, v128
	v_add_f32_e32 v153, 1.0, v124
	v_add_f32_e32 v129, 1.0, v129
	v_add_f32_e32 v155, 1.0, v125
	v_rcp_f32_e32 v122, v126
	v_rcp_f32_e32 v150, v150
	v_rcp_f32_e32 v123, v127
	v_rcp_f32_e32 v124, v128
	v_rcp_f32_e32 v125, v129
	v_rcp_f32_e32 v154, v153
	v_rcp_f32_e32 v155, v155
	v_rcp_f32_e32 v151, v151
	v_pk_mul_f32 v[128:129], v[142:143], v[124:125] op_sel_hi:[0,1]
	v_pk_mul_f32 v[126:127], v[142:143], v[122:123] op_sel_hi:[0,1]
	v_pk_mul_f32 v[124:125], v[142:143], v[154:155] op_sel_hi:[0,1]
	v_pk_mul_f32 v[122:123], v[142:143], v[150:151] op_sel_hi:[0,1]
.LBB0_499:
	v_lshrrev_b32_e32 v150, 2, v143
	s_lshl_b32 s12, s67, 8
	v_and_b32_e32 v150, 64, v150
	v_and_b32_e32 v143, 15, v143
	v_or3_b32 v143, v150, s12, v143
	v_mov_b64_e32 v[150:151], s[34:35]
	v_mad_i64_i32 v[150:151], s[42:43], v143, s78, v[150:151]
	v_cvt_pk_bf16_f32 v126, v126, v127
	v_cvt_pk_bf16_f32 v127, v128, v129
	v_cvt_pk_bf16_f32 v128, v122, v123
	v_cndmask_b32_e64 v122, 0, 1, s[86:87]
	v_lshl_add_u64 v[150:151], v[148:149], 1, v[150:151]
	v_cmp_ne_u32_e64 s[42:43], 1, v122
	s_andn2_b64 vcc, exec, s[86:87]
	v_cvt_pk_bf16_f32 v129, v124, v125
	global_store_dwordx4 v[150:151], v[126:129], off
	s_cbranch_vccnz .LBB0_501
	s_mov_b64 s[12:13], 0x200
	v_lshl_add_u64 v[122:123], v[146:147], 0, s[12:13]
	s_movk_i32 s12, 0xf200
	s_mov_b32 s13, -1
	v_lshl_add_u64 v[124:125], v[144:145], 0, s[12:13]
	v_cndmask_b32_e64 v127, v125, v123, s[40:41]
	v_cndmask_b32_e64 v126, v124, v122, s[40:41]
	v_mov_b32_e32 v122, v194
	v_mov_b32_e32 v123, v195
	v_mov_b32_e32 v124, v196
	v_mov_b32_e32 v125, v197
	v_mov_b32_e32 v126, v198
	v_mov_b32_e32 v127, v199
	v_mov_b32_e32 v128, v200
	v_mov_b32_e32 v129, v201
	v_add_f32_e32 v118, v118, v122
	v_add_f32_e32 v114, v114, v126
	v_add_f32_e32 v119, v119, v123
	v_add_f32_e32 v115, v115, v127
	v_add_f32_e32 v120, v120, v124
	v_add_f32_e32 v116, v116, v128
	v_add_f32_e32 v121, v121, v125
	v_add_f32_e32 v117, v117, v129
	v_mul_f32_e32 v118, 0xbfb8aa3b, v118
	v_mul_f32_e32 v114, 0xbfb8aa3b, v114
	v_mul_f32_e32 v119, 0xbfb8aa3b, v119
	v_mul_f32_e32 v115, 0xbfb8aa3b, v115
	v_mul_f32_e32 v120, 0xbfb8aa3b, v120
	v_mul_f32_e32 v116, 0xbfb8aa3b, v116
	v_mul_f32_e32 v121, 0xbfb8aa3b, v121
	v_mul_f32_e32 v117, 0xbfb8aa3b, v117
	v_exp_f32_e32 v118, v118
	v_exp_f32_e32 v114, v114
	v_exp_f32_e32 v119, v119
	v_exp_f32_e32 v115, v115
	v_exp_f32_e32 v120, v120
	v_exp_f32_e32 v116, v116
	v_exp_f32_e32 v121, v121
	v_exp_f32_e32 v117, v117
	v_add_f32_e32 v118, 1.0, v118
	v_add_f32_e32 v122, 1.0, v114
	v_add_f32_e32 v119, 1.0, v119
	v_add_f32_e32 v123, 1.0, v115
	v_add_f32_e32 v120, 1.0, v120
	v_add_f32_e32 v124, 1.0, v116
	v_add_f32_e32 v121, 1.0, v121
	v_add_f32_e32 v125, 1.0, v117
	v_rcp_f32_e32 v114, v118
	v_rcp_f32_e32 v122, v122
	v_rcp_f32_e32 v115, v119
	v_rcp_f32_e32 v116, v120
	v_rcp_f32_e32 v117, v121
	v_rcp_f32_e32 v124, v124
	v_rcp_f32_e32 v125, v125
	v_rcp_f32_e32 v123, v123
	v_pk_mul_f32 v[120:121], v[142:143], v[116:117] op_sel_hi:[0,1]
	v_pk_mul_f32 v[118:119], v[142:143], v[114:115] op_sel_hi:[0,1]
	v_pk_mul_f32 v[116:117], v[142:143], v[124:125] op_sel_hi:[0,1]
	v_pk_mul_f32 v[114:115], v[142:143], v[122:123] op_sel_hi:[0,1]
; __device__ __forceinline__ unsigned cvt_pk_bf16(float lo, float hi) { unsigned r; asm volatile("v_cvt_pk_bf16_f32 %0, %1, %2" : "=v"(r) : "v"(lo), "v"(hi)); return r; }
; __device__ __forceinline__ float sigmoidf_(float x) { return __builtin_amdgcn_rcpf(1.0f + __expf(-x)); }
;     __device__ __forceinline__ void operator()(f32x4 (&acc)[2][2][4][2], const Unit& u, int wr, int wc, int fr, int fq) const {
;     ...
;                 bf16_t* rowp = O + (size_t)(row0 + ai * HALF + m * 16) * ldc + col0;
; #pragma unroll
;                 for (int bj = 0; bj < 2; ++bj) {
;                     f32x4 v0 = acc[ai][bj][m][0], v1 = acc[ai][bj][m][1];
;                     f(v0, v1, u.pn, col0 + bj * HALF);
;                     u32x4 w; w.x = cvt_pk_bf16(v0[0], v0[1]); w.y = cvt_pk_bf16(v0[2], v0[3]); w.z = cvt_pk_bf16(v1[0], v1[1]); w.w = cvt_pk_bf16(v1[2], v1[3]);
;                     *(u32x4*)(rowp + bj * HALF) = w;
;                 }
;     __device__ __forceinline__ void operator()(f32x4& a, f32x4& b, int pn, int col) const {
;         if (pn < 8) {
;             const float* pp = (pn < 4) ? (w0 + col) : (a0 + col - 1024);
;             const float sc = (pn < 4) ? -0.6065306597126334f : 1.0f;
;             const f32x4 p0 = *(const f32x4*)pp, p1 = *(const f32x4*)(pp + 4);
; #pragma unroll
;             for (int j = 0; j < 4; ++j) { a[j] = sc * sigmoidf_(a[j] + p0[j]); b[j] = sc * sigmoidf_(b[j] + p1[j]); }
;         }
.LBB0_501:
	s_and_b64 vcc, exec, s[42:43]
	v_cvt_pk_bf16_f32 v118, v118, v119
	v_cvt_pk_bf16_f32 v119, v120, v121
	v_cvt_pk_bf16_f32 v120, v114, v115
	v_cvt_pk_bf16_f32 v121, v116, v117
	global_store_dwordx4 v[150:151], v[118:121], off offset:256
	s_cbranch_vccnz .LBB0_503
	s_movk_i32 s12, 0xf000
	s_mov_b32 s13, -1
	v_lshl_add_u64 v[114:115], v[144:145], 0, s[12:13]
	v_cndmask_b32_e64 v119, v115, v147, s[40:41]
	v_cndmask_b32_e64 v118, v114, v146, s[40:41]
	v_mov_b32_e32 v114, v186
	v_mov_b32_e32 v115, v187
	v_mov_b32_e32 v116, v188
	v_mov_b32_e32 v117, v189
	v_mov_b32_e32 v118, v190
	v_mov_b32_e32 v119, v191
	v_mov_b32_e32 v120, v192
	v_mov_b32_e32 v121, v193
	v_add_f32_e32 v110, v110, v114
	v_add_f32_e32 v106, v106, v118
	v_add_f32_e32 v111, v111, v115
	v_add_f32_e32 v107, v107, v119
	v_add_f32_e32 v112, v112, v116
	v_add_f32_e32 v108, v108, v120
	v_add_f32_e32 v113, v113, v117
	v_add_f32_e32 v109, v109, v121
	v_mul_f32_e32 v110, 0xbfb8aa3b, v110
	v_mul_f32_e32 v106, 0xbfb8aa3b, v106
	v_mul_f32_e32 v111, 0xbfb8aa3b, v111
	v_mul_f32_e32 v107, 0xbfb8aa3b, v107
	v_mul_f32_e32 v112, 0xbfb8aa3b, v112
	v_mul_f32_e32 v108, 0xbfb8aa3b, v108
	v_mul_f32_e32 v113, 0xbfb8aa3b, v113
	v_mul_f32_e32 v109, 0xbfb8aa3b, v109
	v_exp_f32_e32 v110, v110
	v_exp_f32_e32 v106, v106
	v_exp_f32_e32 v111, v111
	v_exp_f32_e32 v107, v107
	v_exp_f32_e32 v112, v112
	v_exp_f32_e32 v108, v108
	v_exp_f32_e32 v113, v113
	v_exp_f32_e32 v109, v109
	v_add_f32_e32 v110, 1.0, v110
	v_add_f32_e32 v114, 1.0, v106
	v_add_f32_e32 v111, 1.0, v111
	v_add_f32_e32 v115, 1.0, v107
	v_add_f32_e32 v112, 1.0, v112
	v_add_f32_e32 v116, 1.0, v108
	v_add_f32_e32 v113, 1.0, v113
	v_add_f32_e32 v117, 1.0, v109
	v_rcp_f32_e32 v106, v110
	v_rcp_f32_e32 v114, v114
	v_rcp_f32_e32 v107, v111
	v_rcp_f32_e32 v108, v112
	v_rcp_f32_e32 v109, v113
	v_rcp_f32_e32 v116, v116
	v_rcp_f32_e32 v117, v117
	v_rcp_f32_e32 v115, v115
	v_pk_mul_f32 v[112:113], v[142:143], v[108:109] op_sel_hi:[0,1]
	v_pk_mul_f32 v[110:111], v[142:143], v[106:107] op_sel_hi:[0,1]
	v_pk_mul_f32 v[108:109], v[142:143], v[116:117] op_sel_hi:[0,1]
	v_pk_mul_f32 v[106:107], v[142:143], v[114:115] op_sel_hi:[0,1]
.LBB0_503:
	v_or_b32_e32 v116, 16, v143
	v_mov_b64_e32 v[114:115], s[34:35]
	v_mad_i64_i32 v[114:115], s[44:45], v116, s78, v[114:115]
	v_lshl_add_u64 v[114:115], v[148:149], 1, v[114:115]
	s_and_b64 vcc, exec, s[42:43]
	v_cvt_pk_bf16_f32 v110, v110, v111
	v_cvt_pk_bf16_f32 v111, v112, v113
	v_cvt_pk_bf16_f32 v112, v106, v107
	v_cvt_pk_bf16_f32 v113, v108, v109
	global_store_dwordx4 v[114:115], v[110:113], off
	s_cbranch_vccnz .LBB0_505
	s_mov_b64 s[12:13], 0x200
	v_lshl_add_u64 v[106:107], v[146:147], 0, s[12:13]
	s_movk_i32 s12, 0xf200
	s_mov_b32 s13, -1
	v_lshl_add_u64 v[108:109], v[144:145], 0, s[12:13]
	v_cndmask_b32_e64 v111, v109, v107, s[40:41]
	v_cndmask_b32_e64 v110, v108, v106, s[40:41]
	v_mov_b32_e32 v106, v194
	v_mov_b32_e32 v107, v195
	v_mov_b32_e32 v108, v196
	v_mov_b32_e32 v109, v197
	v_mov_b32_e32 v110, v198
	v_mov_b32_e32 v111, v199
	v_mov_b32_e32 v112, v200
	v_mov_b32_e32 v113, v201
	v_add_f32_e32 v102, v102, v106
	v_add_f32_e32 v98, v98, v110
	v_add_f32_e32 v103, v103, v107
	v_add_f32_e32 v99, v99, v111
	v_add_f32_e32 v104, v104, v108
	v_add_f32_e32 v100, v100, v112
	v_add_f32_e32 v105, v105, v109
	v_add_f32_e32 v101, v101, v113
	v_mul_f32_e32 v102, 0xbfb8aa3b, v102
	v_mul_f32_e32 v98, 0xbfb8aa3b, v98
	v_mul_f32_e32 v103, 0xbfb8aa3b, v103
	v_mul_f32_e32 v99, 0xbfb8aa3b, v99
	v_mul_f32_e32 v104, 0xbfb8aa3b, v104
	v_mul_f32_e32 v100, 0xbfb8aa3b, v100
	v_mul_f32_e32 v105, 0xbfb8aa3b, v105
	v_mul_f32_e32 v101, 0xbfb8aa3b, v101
	v_exp_f32_e32 v102, v102
	v_exp_f32_e32 v98, v98
	v_exp_f32_e32 v103, v103
	v_exp_f32_e32 v99, v99
	v_exp_f32_e32 v104, v104
	v_exp_f32_e32 v100, v100
	v_exp_f32_e32 v105, v105
	v_exp_f32_e32 v101, v101
	v_add_f32_e32 v102, 1.0, v102
	v_add_f32_e32 v106, 1.0, v98
	v_add_f32_e32 v103, 1.0, v103
	v_add_f32_e32 v107, 1.0, v99
	v_add_f32_e32 v104, 1.0, v104
	v_add_f32_e32 v108, 1.0, v100
	v_add_f32_e32 v105, 1.0, v105
	v_add_f32_e32 v109, 1.0, v101
	v_rcp_f32_e32 v98, v102
	v_rcp_f32_e32 v106, v106
	v_rcp_f32_e32 v99, v103
	v_rcp_f32_e32 v100, v104
	v_rcp_f32_e32 v101, v105
	v_rcp_f32_e32 v108, v108
	v_rcp_f32_e32 v109, v109
	v_rcp_f32_e32 v107, v107
	v_pk_mul_f32 v[104:105], v[142:143], v[100:101] op_sel_hi:[0,1]
	v_pk_mul_f32 v[102:103], v[142:143], v[98:99] op_sel_hi:[0,1]
	v_pk_mul_f32 v[100:101], v[142:143], v[108:109] op_sel_hi:[0,1]
	v_pk_mul_f32 v[98:99], v[142:143], v[106:107] op_sel_hi:[0,1]
.LBB0_505:
	s_and_b64 vcc, exec, s[42:43]
	v_cvt_pk_bf16_f32 v102, v102, v103
	v_cvt_pk_bf16_f32 v103, v104, v105
	v_cvt_pk_bf16_f32 v104, v98, v99
	v_cvt_pk_bf16_f32 v105, v100, v101
	global_store_dwordx4 v[114:115], v[102:105], off offset:256
	s_cbranch_vccnz .LBB0_507
	s_movk_i32 s12, 0xf000
	s_mov_b32 s13, -1
	v_lshl_add_u64 v[98:99], v[144:145], 0, s[12:13]
	v_cndmask_b32_e64 v103, v99, v147, s[40:41]
	v_cndmask_b32_e64 v102, v98, v146, s[40:41]
	v_mov_b32_e32 v98, v186
	v_mov_b32_e32 v99, v187
	v_mov_b32_e32 v100, v188
	v_mov_b32_e32 v101, v189
	v_mov_b32_e32 v102, v190
	v_mov_b32_e32 v103, v191
	v_mov_b32_e32 v104, v192
	v_mov_b32_e32 v105, v193
	v_add_f32_e32 v94, v94, v98
	v_add_f32_e32 v90, v90, v102
	v_add_f32_e32 v95, v95, v99
	v_add_f32_e32 v91, v91, v103
	v_add_f32_e32 v96, v96, v100
	v_add_f32_e32 v92, v92, v104
	v_add_f32_e32 v97, v97, v101
	v_add_f32_e32 v93, v93, v105
	v_mul_f32_e32 v94, 0xbfb8aa3b, v94
	v_mul_f32_e32 v90, 0xbfb8aa3b, v90
	v_mul_f32_e32 v95, 0xbfb8aa3b, v95
	v_mul_f32_e32 v91, 0xbfb8aa3b, v91
	v_mul_f32_e32 v96, 0xbfb8aa3b, v96
	v_mul_f32_e32 v92, 0xbfb8aa3b, v92
	v_mul_f32_e32 v97, 0xbfb8aa3b, v97
	v_mul_f32_e32 v93, 0xbfb8aa3b, v93
	v_exp_f32_e32 v94, v94
	v_exp_f32_e32 v90, v90
	v_exp_f32_e32 v95, v95
	v_exp_f32_e32 v91, v91
	v_exp_f32_e32 v96, v96
	v_exp_f32_e32 v92, v92
	v_exp_f32_e32 v97, v97
	v_exp_f32_e32 v93, v93
	v_add_f32_e32 v94, 1.0, v94
	v_add_f32_e32 v98, 1.0, v90
	v_add_f32_e32 v95, 1.0, v95
	v_add_f32_e32 v99, 1.0, v91
	v_add_f32_e32 v96, 1.0, v96
	v_add_f32_e32 v100, 1.0, v92
	v_add_f32_e32 v97, 1.0, v97
	v_add_f32_e32 v101, 1.0, v93
	v_rcp_f32_e32 v90, v94
	v_rcp_f32_e32 v98, v98
	v_rcp_f32_e32 v91, v95
	v_rcp_f32_e32 v92, v96
	v_rcp_f32_e32 v93, v97
	v_rcp_f32_e32 v100, v100
	v_rcp_f32_e32 v101, v101
	v_rcp_f32_e32 v99, v99
	v_pk_mul_f32 v[96:97], v[142:143], v[92:93] op_sel_hi:[0,1]
	v_pk_mul_f32 v[94:95], v[142:143], v[90:91] op_sel_hi:[0,1]
	v_pk_mul_f32 v[92:93], v[142:143], v[100:101] op_sel_hi:[0,1]
	v_pk_mul_f32 v[90:91], v[142:143], v[98:99] op_sel_hi:[0,1]
; __device__ __forceinline__ unsigned cvt_pk_bf16(float lo, float hi) { unsigned r; asm volatile("v_cvt_pk_bf16_f32 %0, %1, %2" : "=v"(r) : "v"(lo), "v"(hi)); return r; }
; __device__ __forceinline__ float sigmoidf_(float x) { return __builtin_amdgcn_rcpf(1.0f + __expf(-x)); }
;     __device__ __forceinline__ void operator()(f32x4 (&acc)[2][2][4][2], const Unit& u, int wr, int wc, int fr, int fq) const {
;     ...
;                 bf16_t* rowp = O + (size_t)(row0 + ai * HALF + m * 16) * ldc + col0;
; #pragma unroll
;                 for (int bj = 0; bj < 2; ++bj) {
;                     f32x4 v0 = acc[ai][bj][m][0], v1 = acc[ai][bj][m][1];
;                     f(v0, v1, u.pn, col0 + bj * HALF);
;                     u32x4 w; w.x = cvt_pk_bf16(v0[0], v0[1]); w.y = cvt_pk_bf16(v0[2], v0[3]); w.z = cvt_pk_bf16(v1[0], v1[1]); w.w = cvt_pk_bf16(v1[2], v1[3]);
;                     *(u32x4*)(rowp + bj * HALF) = w;
;                 }
;     __device__ __forceinline__ void operator()(f32x4& a, f32x4& b, int pn, int col) const {
;         if (pn < 8) {
;             const float* pp = (pn < 4) ? (w0 + col) : (a0 + col - 1024);
;             const float sc = (pn < 4) ? -0.6065306597126334f : 1.0f;
;             const f32x4 p0 = *(const f32x4*)pp, p1 = *(const f32x4*)(pp + 4);
; #pragma unroll
;             for (int j = 0; j < 4; ++j) { a[j] = sc * sigmoidf_(a[j] + p0[j]); b[j] = sc * sigmoidf_(b[j] + p1[j]); }
;         }
.LBB0_507:
	v_or_b32_e32 v100, 32, v143
	v_mov_b64_e32 v[98:99], s[34:35]
	v_mad_i64_i32 v[98:99], s[44:45], v100, s78, v[98:99]
	v_lshl_add_u64 v[98:99], v[148:149], 1, v[98:99]
	s_and_b64 vcc, exec, s[42:43]
	v_cvt_pk_bf16_f32 v94, v94, v95
	v_cvt_pk_bf16_f32 v95, v96, v97
	v_cvt_pk_bf16_f32 v96, v90, v91
	v_cvt_pk_bf16_f32 v97, v92, v93
	global_store_dwordx4 v[98:99], v[94:97], off
	s_cbranch_vccnz .LBB0_509
	s_mov_b64 s[12:13], 0x200
	v_lshl_add_u64 v[90:91], v[146:147], 0, s[12:13]
	s_movk_i32 s12, 0xf200
	s_mov_b32 s13, -1
	v_lshl_add_u64 v[92:93], v[144:145], 0, s[12:13]
	v_cndmask_b32_e64 v95, v93, v91, s[40:41]
	v_cndmask_b32_e64 v94, v92, v90, s[40:41]
	v_mov_b32_e32 v90, v194
	v_mov_b32_e32 v91, v195
	v_mov_b32_e32 v92, v196
	v_mov_b32_e32 v93, v197
	v_mov_b32_e32 v94, v198
	v_mov_b32_e32 v95, v199
	v_mov_b32_e32 v96, v200
	v_mov_b32_e32 v97, v201
	v_add_f32_e32 v86, v86, v90
	v_add_f32_e32 v82, v82, v94
	v_add_f32_e32 v87, v87, v91
	v_add_f32_e32 v83, v83, v95
	v_add_f32_e32 v88, v88, v92
	v_add_f32_e32 v84, v84, v96
	v_add_f32_e32 v89, v89, v93
	v_add_f32_e32 v85, v85, v97
	v_mul_f32_e32 v86, 0xbfb8aa3b, v86
	v_mul_f32_e32 v82, 0xbfb8aa3b, v82
	v_mul_f32_e32 v87, 0xbfb8aa3b, v87
	v_mul_f32_e32 v83, 0xbfb8aa3b, v83
	v_mul_f32_e32 v88, 0xbfb8aa3b, v88
	v_mul_f32_e32 v84, 0xbfb8aa3b, v84
	v_mul_f32_e32 v89, 0xbfb8aa3b, v89
	v_mul_f32_e32 v85, 0xbfb8aa3b, v85
	v_exp_f32_e32 v86, v86
	v_exp_f32_e32 v82, v82
	v_exp_f32_e32 v87, v87
	v_exp_f32_e32 v83, v83
	v_exp_f32_e32 v88, v88
	v_exp_f32_e32 v84, v84
	v_exp_f32_e32 v89, v89
	v_exp_f32_e32 v85, v85
	v_add_f32_e32 v86, 1.0, v86
	v_add_f32_e32 v90, 1.0, v82
	v_add_f32_e32 v87, 1.0, v87
	v_add_f32_e32 v91, 1.0, v83
	v_add_f32_e32 v88, 1.0, v88
	v_add_f32_e32 v92, 1.0, v84
	v_add_f32_e32 v89, 1.0, v89
	v_add_f32_e32 v93, 1.0, v85
	v_rcp_f32_e32 v82, v86
	v_rcp_f32_e32 v90, v90
	v_rcp_f32_e32 v83, v87
	v_rcp_f32_e32 v84, v88
	v_rcp_f32_e32 v85, v89
	v_rcp_f32_e32 v92, v92
	v_rcp_f32_e32 v93, v93
	v_rcp_f32_e32 v91, v91
	v_pk_mul_f32 v[88:89], v[142:143], v[84:85] op_sel_hi:[0,1]
	v_pk_mul_f32 v[86:87], v[142:143], v[82:83] op_sel_hi:[0,1]
	v_pk_mul_f32 v[84:85], v[142:143], v[92:93] op_sel_hi:[0,1]
	v_pk_mul_f32 v[82:83], v[142:143], v[90:91] op_sel_hi:[0,1]
.LBB0_509:
	s_and_b64 vcc, exec, s[42:43]
	v_cvt_pk_bf16_f32 v86, v86, v87
	v_cvt_pk_bf16_f32 v87, v88, v89
	v_cvt_pk_bf16_f32 v88, v82, v83
	v_cvt_pk_bf16_f32 v89, v84, v85
	global_store_dwordx4 v[98:99], v[86:89], off offset:256
	s_cbranch_vccnz .LBB0_511
	s_movk_i32 s12, 0xf000
	s_mov_b32 s13, -1
	v_lshl_add_u64 v[82:83], v[144:145], 0, s[12:13]
	v_cndmask_b32_e64 v87, v83, v147, s[40:41]
	v_cndmask_b32_e64 v86, v82, v146, s[40:41]
	v_mov_b32_e32 v82, v186
	v_mov_b32_e32 v83, v187
	v_mov_b32_e32 v84, v188
	v_mov_b32_e32 v85, v189
	v_mov_b32_e32 v86, v190
	v_mov_b32_e32 v87, v191
	v_mov_b32_e32 v88, v192
	v_mov_b32_e32 v89, v193
	v_add_f32_e32 v78, v78, v82
	v_add_f32_e32 v74, v74, v86
	v_add_f32_e32 v79, v79, v83
	v_add_f32_e32 v75, v75, v87
	v_add_f32_e32 v80, v80, v84
	v_add_f32_e32 v76, v76, v88
	v_add_f32_e32 v81, v81, v85
	v_add_f32_e32 v77, v77, v89
	v_mul_f32_e32 v78, 0xbfb8aa3b, v78
	v_mul_f32_e32 v74, 0xbfb8aa3b, v74
	v_mul_f32_e32 v79, 0xbfb8aa3b, v79
	v_mul_f32_e32 v75, 0xbfb8aa3b, v75
	v_mul_f32_e32 v80, 0xbfb8aa3b, v80
	v_mul_f32_e32 v76, 0xbfb8aa3b, v76
	v_mul_f32_e32 v81, 0xbfb8aa3b, v81
	v_mul_f32_e32 v77, 0xbfb8aa3b, v77
	v_exp_f32_e32 v78, v78
	v_exp_f32_e32 v74, v74
	v_exp_f32_e32 v79, v79
	v_exp_f32_e32 v75, v75
	v_exp_f32_e32 v80, v80
	v_exp_f32_e32 v76, v76
	v_exp_f32_e32 v81, v81
	v_exp_f32_e32 v77, v77
	v_add_f32_e32 v78, 1.0, v78
	v_add_f32_e32 v82, 1.0, v74
	v_add_f32_e32 v79, 1.0, v79
	v_add_f32_e32 v83, 1.0, v75
	v_add_f32_e32 v80, 1.0, v80
	v_add_f32_e32 v84, 1.0, v76
	v_add_f32_e32 v81, 1.0, v81
	v_add_f32_e32 v85, 1.0, v77
	v_rcp_f32_e32 v74, v78
	v_rcp_f32_e32 v82, v82
	v_rcp_f32_e32 v75, v79
	v_rcp_f32_e32 v76, v80
	v_rcp_f32_e32 v77, v81
	v_rcp_f32_e32 v84, v84
	v_rcp_f32_e32 v85, v85
	v_rcp_f32_e32 v83, v83
	v_pk_mul_f32 v[80:81], v[142:143], v[76:77] op_sel_hi:[0,1]
	v_pk_mul_f32 v[78:79], v[142:143], v[74:75] op_sel_hi:[0,1]
	v_pk_mul_f32 v[76:77], v[142:143], v[84:85] op_sel_hi:[0,1]
	v_pk_mul_f32 v[74:75], v[142:143], v[82:83] op_sel_hi:[0,1]
.LBB0_511:
	v_or_b32_e32 v84, 48, v143
	v_mov_b64_e32 v[82:83], s[34:35]
	v_mad_i64_i32 v[82:83], s[44:45], v84, s78, v[82:83]
	v_lshl_add_u64 v[82:83], v[148:149], 1, v[82:83]
	s_and_b64 vcc, exec, s[42:43]
	v_cvt_pk_bf16_f32 v78, v78, v79
	v_cvt_pk_bf16_f32 v79, v80, v81
	v_cvt_pk_bf16_f32 v80, v74, v75
	v_cvt_pk_bf16_f32 v81, v76, v77
	global_store_dwordx4 v[82:83], v[78:81], off
	s_cbranch_vccnz .LBB0_513
	s_mov_b64 s[12:13], 0x200
	v_lshl_add_u64 v[74:75], v[146:147], 0, s[12:13]
	s_movk_i32 s12, 0xf200
	s_mov_b32 s13, -1
	v_lshl_add_u64 v[76:77], v[144:145], 0, s[12:13]
	v_cndmask_b32_e64 v79, v77, v75, s[40:41]
	v_cndmask_b32_e64 v78, v76, v74, s[40:41]
	v_mov_b32_e32 v74, v194
	v_mov_b32_e32 v75, v195
	v_mov_b32_e32 v76, v196
	v_mov_b32_e32 v77, v197
	v_mov_b32_e32 v78, v198
	v_mov_b32_e32 v79, v199
	v_mov_b32_e32 v80, v200
	v_mov_b32_e32 v81, v201
	v_add_f32_e32 v70, v70, v74
	v_add_f32_e32 v66, v66, v78
	v_add_f32_e32 v71, v71, v75
	v_add_f32_e32 v67, v67, v79
	v_add_f32_e32 v72, v72, v76
	v_add_f32_e32 v68, v68, v80
	v_add_f32_e32 v73, v73, v77
	v_add_f32_e32 v69, v69, v81
	v_mul_f32_e32 v70, 0xbfb8aa3b, v70
	v_mul_f32_e32 v66, 0xbfb8aa3b, v66
	v_mul_f32_e32 v71, 0xbfb8aa3b, v71
	v_mul_f32_e32 v67, 0xbfb8aa3b, v67
	v_mul_f32_e32 v72, 0xbfb8aa3b, v72
	v_mul_f32_e32 v68, 0xbfb8aa3b, v68
	v_mul_f32_e32 v73, 0xbfb8aa3b, v73
	v_mul_f32_e32 v69, 0xbfb8aa3b, v69
	v_exp_f32_e32 v70, v70
	v_exp_f32_e32 v66, v66
	v_exp_f32_e32 v71, v71
	v_exp_f32_e32 v67, v67
	v_exp_f32_e32 v72, v72
	v_exp_f32_e32 v68, v68
	v_exp_f32_e32 v73, v73
	v_exp_f32_e32 v69, v69
	v_add_f32_e32 v70, 1.0, v70
	v_add_f32_e32 v74, 1.0, v66
	v_add_f32_e32 v71, 1.0, v71
	v_add_f32_e32 v75, 1.0, v67
	v_add_f32_e32 v72, 1.0, v72
	v_add_f32_e32 v76, 1.0, v68
	v_add_f32_e32 v73, 1.0, v73
	v_add_f32_e32 v77, 1.0, v69
	v_rcp_f32_e32 v66, v70
	v_rcp_f32_e32 v74, v74
	v_rcp_f32_e32 v67, v71
	v_rcp_f32_e32 v68, v72
	v_rcp_f32_e32 v69, v73
	v_rcp_f32_e32 v76, v76
	v_rcp_f32_e32 v77, v77
	v_rcp_f32_e32 v75, v75
	v_pk_mul_f32 v[72:73], v[142:143], v[68:69] op_sel_hi:[0,1]
	v_pk_mul_f32 v[70:71], v[142:143], v[66:67] op_sel_hi:[0,1]
	v_pk_mul_f32 v[68:69], v[142:143], v[76:77] op_sel_hi:[0,1]
	v_pk_mul_f32 v[66:67], v[142:143], v[74:75] op_sel_hi:[0,1]
; __device__ __forceinline__ unsigned cvt_pk_bf16(float lo, float hi) { unsigned r; asm volatile("v_cvt_pk_bf16_f32 %0, %1, %2" : "=v"(r) : "v"(lo), "v"(hi)); return r; }
; __device__ __forceinline__ float sigmoidf_(float x) { return __builtin_amdgcn_rcpf(1.0f + __expf(-x)); }
;     __device__ __forceinline__ void operator()(f32x4 (&acc)[2][2][4][2], const Unit& u, int wr, int wc, int fr, int fq) const {
;     ...
;                 bf16_t* rowp = O + (size_t)(row0 + ai * HALF + m * 16) * ldc + col0;
; #pragma unroll
;                 for (int bj = 0; bj < 2; ++bj) {
;                     f32x4 v0 = acc[ai][bj][m][0], v1 = acc[ai][bj][m][1];
;                     f(v0, v1, u.pn, col0 + bj * HALF);
;                     u32x4 w; w.x = cvt_pk_bf16(v0[0], v0[1]); w.y = cvt_pk_bf16(v0[2], v0[3]); w.z = cvt_pk_bf16(v1[0], v1[1]); w.w = cvt_pk_bf16(v1[2], v1[3]);
;                     *(u32x4*)(rowp + bj * HALF) = w;
;                 }
;     __device__ __forceinline__ void operator()(f32x4& a, f32x4& b, int pn, int col) const {
;         if (pn < 8) {
;             const float* pp = (pn < 4) ? (w0 + col) : (a0 + col - 1024);
;             const float sc = (pn < 4) ? -0.6065306597126334f : 1.0f;
;             const f32x4 p0 = *(const f32x4*)pp, p1 = *(const f32x4*)(pp + 4);
; #pragma unroll
;             for (int j = 0; j < 4; ++j) { a[j] = sc * sigmoidf_(a[j] + p0[j]); b[j] = sc * sigmoidf_(b[j] + p1[j]); }
;         }
.LBB0_513:
	s_and_b64 vcc, exec, s[42:43]
	v_cvt_pk_bf16_f32 v70, v70, v71
	v_cvt_pk_bf16_f32 v71, v72, v73
	v_cvt_pk_bf16_f32 v72, v66, v67
	v_cvt_pk_bf16_f32 v73, v68, v69
	global_store_dwordx4 v[82:83], v[70:73], off offset:256
	s_cbranch_vccnz .LBB0_515
	s_movk_i32 s12, 0xf000
	s_mov_b32 s13, -1
	v_lshl_add_u64 v[66:67], v[144:145], 0, s[12:13]
	v_cndmask_b32_e64 v71, v67, v147, s[40:41]
	v_cndmask_b32_e64 v70, v66, v146, s[40:41]
	v_mov_b32_e32 v66, v186
	v_mov_b32_e32 v67, v187
	v_mov_b32_e32 v68, v188
	v_mov_b32_e32 v69, v189
	v_mov_b32_e32 v70, v190
	v_mov_b32_e32 v71, v191
	v_mov_b32_e32 v72, v192
	v_mov_b32_e32 v73, v193
	v_add_f32_e32 v62, v62, v66
	v_add_f32_e32 v58, v58, v70
	v_add_f32_e32 v63, v63, v67
	v_add_f32_e32 v59, v59, v71
	v_add_f32_e32 v64, v64, v68
	v_add_f32_e32 v60, v60, v72
	v_add_f32_e32 v65, v65, v69
	v_add_f32_e32 v61, v61, v73
	v_mul_f32_e32 v62, 0xbfb8aa3b, v62
	v_mul_f32_e32 v58, 0xbfb8aa3b, v58
	v_mul_f32_e32 v63, 0xbfb8aa3b, v63
	v_mul_f32_e32 v59, 0xbfb8aa3b, v59
	v_mul_f32_e32 v64, 0xbfb8aa3b, v64
	v_mul_f32_e32 v60, 0xbfb8aa3b, v60
	v_mul_f32_e32 v65, 0xbfb8aa3b, v65
	v_mul_f32_e32 v61, 0xbfb8aa3b, v61
	v_exp_f32_e32 v62, v62
	v_exp_f32_e32 v58, v58
	v_exp_f32_e32 v63, v63
	v_exp_f32_e32 v59, v59
	v_exp_f32_e32 v64, v64
	v_exp_f32_e32 v60, v60
	v_exp_f32_e32 v65, v65
	v_exp_f32_e32 v61, v61
	v_add_f32_e32 v62, 1.0, v62
	v_add_f32_e32 v66, 1.0, v58
	v_add_f32_e32 v63, 1.0, v63
	v_add_f32_e32 v67, 1.0, v59
	v_add_f32_e32 v64, 1.0, v64
	v_add_f32_e32 v68, 1.0, v60
	v_add_f32_e32 v65, 1.0, v65
	v_add_f32_e32 v69, 1.0, v61
	v_rcp_f32_e32 v58, v62
	v_rcp_f32_e32 v66, v66
	v_rcp_f32_e32 v59, v63
	v_rcp_f32_e32 v60, v64
	v_rcp_f32_e32 v61, v65
	v_rcp_f32_e32 v68, v68
	v_rcp_f32_e32 v69, v69
	v_rcp_f32_e32 v67, v67
	v_pk_mul_f32 v[64:65], v[142:143], v[60:61] op_sel_hi:[0,1]
	v_pk_mul_f32 v[62:63], v[142:143], v[58:59] op_sel_hi:[0,1]
	v_pk_mul_f32 v[60:61], v[142:143], v[68:69] op_sel_hi:[0,1]
	v_pk_mul_f32 v[58:59], v[142:143], v[66:67] op_sel_hi:[0,1]
.LBB0_515:
	v_or_b32_e32 v68, 0x80, v143
	v_mov_b64_e32 v[66:67], s[34:35]
	v_mad_i64_i32 v[66:67], s[44:45], v68, s78, v[66:67]
	v_lshl_add_u64 v[66:67], v[148:149], 1, v[66:67]
	s_and_b64 vcc, exec, s[42:43]
	v_cvt_pk_bf16_f32 v62, v62, v63
	v_cvt_pk_bf16_f32 v63, v64, v65
	v_cvt_pk_bf16_f32 v64, v58, v59
	v_cvt_pk_bf16_f32 v65, v60, v61
	global_store_dwordx4 v[66:67], v[62:65], off
	s_cbranch_vccnz .LBB0_517
	s_mov_b64 s[12:13], 0x200
	v_lshl_add_u64 v[58:59], v[146:147], 0, s[12:13]
	s_movk_i32 s12, 0xf200
	s_mov_b32 s13, -1
	v_lshl_add_u64 v[60:61], v[144:145], 0, s[12:13]
	v_cndmask_b32_e64 v63, v61, v59, s[40:41]
	v_cndmask_b32_e64 v62, v60, v58, s[40:41]
	v_mov_b32_e32 v58, v194
	v_mov_b32_e32 v59, v195
	v_mov_b32_e32 v60, v196
	v_mov_b32_e32 v61, v197
	v_mov_b32_e32 v62, v198
	v_mov_b32_e32 v63, v199
	v_mov_b32_e32 v64, v200
	v_mov_b32_e32 v65, v201
	v_add_f32_e32 v54, v54, v58
	v_add_f32_e32 v50, v50, v62
	v_add_f32_e32 v55, v55, v59
	v_add_f32_e32 v51, v51, v63
	v_add_f32_e32 v56, v56, v60
	v_add_f32_e32 v52, v52, v64
	v_add_f32_e32 v57, v57, v61
	v_add_f32_e32 v53, v53, v65
	v_mul_f32_e32 v54, 0xbfb8aa3b, v54
	v_mul_f32_e32 v50, 0xbfb8aa3b, v50
	v_mul_f32_e32 v55, 0xbfb8aa3b, v55
	v_mul_f32_e32 v51, 0xbfb8aa3b, v51
	v_mul_f32_e32 v56, 0xbfb8aa3b, v56
	v_mul_f32_e32 v52, 0xbfb8aa3b, v52
	v_mul_f32_e32 v57, 0xbfb8aa3b, v57
	v_mul_f32_e32 v53, 0xbfb8aa3b, v53
	v_exp_f32_e32 v54, v54
	v_exp_f32_e32 v50, v50
	v_exp_f32_e32 v55, v55
	v_exp_f32_e32 v51, v51
	v_exp_f32_e32 v56, v56
	v_exp_f32_e32 v52, v52
	v_exp_f32_e32 v57, v57
	v_exp_f32_e32 v53, v53
	v_add_f32_e32 v54, 1.0, v54
	v_add_f32_e32 v58, 1.0, v50
	v_add_f32_e32 v55, 1.0, v55
	v_add_f32_e32 v59, 1.0, v51
	v_add_f32_e32 v56, 1.0, v56
	v_add_f32_e32 v60, 1.0, v52
	v_add_f32_e32 v57, 1.0, v57
	v_add_f32_e32 v61, 1.0, v53
	v_rcp_f32_e32 v50, v54
	v_rcp_f32_e32 v58, v58
	v_rcp_f32_e32 v51, v55
	v_rcp_f32_e32 v52, v56
	v_rcp_f32_e32 v53, v57
	v_rcp_f32_e32 v60, v60
	v_rcp_f32_e32 v61, v61
	v_rcp_f32_e32 v59, v59
	v_pk_mul_f32 v[56:57], v[142:143], v[52:53] op_sel_hi:[0,1]
	v_pk_mul_f32 v[54:55], v[142:143], v[50:51] op_sel_hi:[0,1]
	v_pk_mul_f32 v[52:53], v[142:143], v[60:61] op_sel_hi:[0,1]
	v_pk_mul_f32 v[50:51], v[142:143], v[58:59] op_sel_hi:[0,1]
.LBB0_517:
	s_and_b64 vcc, exec, s[42:43]
	v_cvt_pk_bf16_f32 v54, v54, v55
	v_cvt_pk_bf16_f32 v55, v56, v57
	v_cvt_pk_bf16_f32 v56, v50, v51
	v_cvt_pk_bf16_f32 v57, v52, v53
	global_store_dwordx4 v[66:67], v[54:57], off offset:256
	s_cbranch_vccnz .LBB0_519
	s_movk_i32 s12, 0xf000
	s_mov_b32 s13, -1
	v_lshl_add_u64 v[50:51], v[144:145], 0, s[12:13]
	v_cndmask_b32_e64 v55, v51, v147, s[40:41]
	v_cndmask_b32_e64 v54, v50, v146, s[40:41]
	v_mov_b32_e32 v50, v186
	v_mov_b32_e32 v51, v187
	v_mov_b32_e32 v52, v188
	v_mov_b32_e32 v53, v189
	v_mov_b32_e32 v54, v190
	v_mov_b32_e32 v55, v191
	v_mov_b32_e32 v56, v192
	v_mov_b32_e32 v57, v193
	v_add_f32_e32 v46, v46, v50
	v_add_f32_e32 v42, v42, v54
	v_add_f32_e32 v47, v47, v51
	v_add_f32_e32 v43, v43, v55
	v_add_f32_e32 v48, v48, v52
	v_add_f32_e32 v44, v44, v56
	v_add_f32_e32 v49, v49, v53
	v_add_f32_e32 v45, v45, v57
	v_mul_f32_e32 v46, 0xbfb8aa3b, v46
	v_mul_f32_e32 v42, 0xbfb8aa3b, v42
	v_mul_f32_e32 v47, 0xbfb8aa3b, v47
	v_mul_f32_e32 v43, 0xbfb8aa3b, v43
	v_mul_f32_e32 v48, 0xbfb8aa3b, v48
	v_mul_f32_e32 v44, 0xbfb8aa3b, v44
	v_mul_f32_e32 v49, 0xbfb8aa3b, v49
	v_mul_f32_e32 v45, 0xbfb8aa3b, v45
	v_exp_f32_e32 v46, v46
	v_exp_f32_e32 v42, v42
	v_exp_f32_e32 v47, v47
	v_exp_f32_e32 v43, v43
	v_exp_f32_e32 v48, v48
	v_exp_f32_e32 v44, v44
	v_exp_f32_e32 v49, v49
	v_exp_f32_e32 v45, v45
	v_add_f32_e32 v46, 1.0, v46
	v_add_f32_e32 v50, 1.0, v42
	v_add_f32_e32 v47, 1.0, v47
	v_add_f32_e32 v51, 1.0, v43
	v_add_f32_e32 v48, 1.0, v48
	v_add_f32_e32 v52, 1.0, v44
	v_add_f32_e32 v49, 1.0, v49
	v_add_f32_e32 v53, 1.0, v45
	v_rcp_f32_e32 v42, v46
	v_rcp_f32_e32 v50, v50
	v_rcp_f32_e32 v43, v47
	v_rcp_f32_e32 v44, v48
	v_rcp_f32_e32 v45, v49
	v_rcp_f32_e32 v52, v52
	v_rcp_f32_e32 v53, v53
	v_rcp_f32_e32 v51, v51
	v_pk_mul_f32 v[48:49], v[142:143], v[44:45] op_sel_hi:[0,1]
	v_pk_mul_f32 v[46:47], v[142:143], v[42:43] op_sel_hi:[0,1]
	v_pk_mul_f32 v[44:45], v[142:143], v[52:53] op_sel_hi:[0,1]
	v_pk_mul_f32 v[42:43], v[142:143], v[50:51] op_sel_hi:[0,1]
; __device__ __forceinline__ unsigned cvt_pk_bf16(float lo, float hi) { unsigned r; asm volatile("v_cvt_pk_bf16_f32 %0, %1, %2" : "=v"(r) : "v"(lo), "v"(hi)); return r; }
; __device__ __forceinline__ float sigmoidf_(float x) { return __builtin_amdgcn_rcpf(1.0f + __expf(-x)); }
;     __device__ __forceinline__ void operator()(f32x4 (&acc)[2][2][4][2], const Unit& u, int wr, int wc, int fr, int fq) const {
;     ...
;                 bf16_t* rowp = O + (size_t)(row0 + ai * HALF + m * 16) * ldc + col0;
; #pragma unroll
;                 for (int bj = 0; bj < 2; ++bj) {
;                     f32x4 v0 = acc[ai][bj][m][0], v1 = acc[ai][bj][m][1];
;                     f(v0, v1, u.pn, col0 + bj * HALF);
;                     u32x4 w; w.x = cvt_pk_bf16(v0[0], v0[1]); w.y = cvt_pk_bf16(v0[2], v0[3]); w.z = cvt_pk_bf16(v1[0], v1[1]); w.w = cvt_pk_bf16(v1[2], v1[3]);
;                     *(u32x4*)(rowp + bj * HALF) = w;
;                 }
;     __device__ __forceinline__ void operator()(f32x4& a, f32x4& b, int pn, int col) const {
;         if (pn < 8) {
;             const float* pp = (pn < 4) ? (w0 + col) : (a0 + col - 1024);
;             const float sc = (pn < 4) ? -0.6065306597126334f : 1.0f;
;             const f32x4 p0 = *(const f32x4*)pp, p1 = *(const f32x4*)(pp + 4);
; #pragma unroll
;             for (int j = 0; j < 4; ++j) { a[j] = sc * sigmoidf_(a[j] + p0[j]); b[j] = sc * sigmoidf_(b[j] + p1[j]); }
;         }
.LBB0_519:
	v_or_b32_e32 v52, 0x90, v143
	v_mov_b64_e32 v[50:51], s[34:35]
	v_mad_i64_i32 v[50:51], s[44:45], v52, s78, v[50:51]
	v_lshl_add_u64 v[50:51], v[148:149], 1, v[50:51]
	s_and_b64 vcc, exec, s[42:43]
	v_cvt_pk_bf16_f32 v46, v46, v47
	v_cvt_pk_bf16_f32 v47, v48, v49
	v_cvt_pk_bf16_f32 v48, v42, v43
	v_cvt_pk_bf16_f32 v49, v44, v45
	global_store_dwordx4 v[50:51], v[46:49], off
	s_cbranch_vccnz .LBB0_521
	s_mov_b64 s[12:13], 0x200
	v_lshl_add_u64 v[42:43], v[146:147], 0, s[12:13]
	s_movk_i32 s12, 0xf200
	s_mov_b32 s13, -1
	v_lshl_add_u64 v[44:45], v[144:145], 0, s[12:13]
	v_cndmask_b32_e64 v47, v45, v43, s[40:41]
	v_cndmask_b32_e64 v46, v44, v42, s[40:41]
	v_mov_b32_e32 v42, v194
	v_mov_b32_e32 v43, v195
	v_mov_b32_e32 v44, v196
	v_mov_b32_e32 v45, v197
	v_mov_b32_e32 v46, v198
	v_mov_b32_e32 v47, v199
	v_mov_b32_e32 v48, v200
	v_mov_b32_e32 v49, v201
	v_add_f32_e32 v38, v38, v42
	v_add_f32_e32 v34, v34, v46
	v_add_f32_e32 v39, v39, v43
	v_add_f32_e32 v35, v35, v47
	v_add_f32_e32 v40, v40, v44
	v_add_f32_e32 v36, v36, v48
	v_add_f32_e32 v41, v41, v45
	v_add_f32_e32 v37, v37, v49
	v_mul_f32_e32 v38, 0xbfb8aa3b, v38
	v_mul_f32_e32 v34, 0xbfb8aa3b, v34
	v_mul_f32_e32 v39, 0xbfb8aa3b, v39
	v_mul_f32_e32 v35, 0xbfb8aa3b, v35
	v_mul_f32_e32 v40, 0xbfb8aa3b, v40
	v_mul_f32_e32 v36, 0xbfb8aa3b, v36
	v_mul_f32_e32 v41, 0xbfb8aa3b, v41
	v_mul_f32_e32 v37, 0xbfb8aa3b, v37
	v_exp_f32_e32 v38, v38
	v_exp_f32_e32 v34, v34
	v_exp_f32_e32 v39, v39
	v_exp_f32_e32 v35, v35
	v_exp_f32_e32 v40, v40
	v_exp_f32_e32 v36, v36
	v_exp_f32_e32 v41, v41
	v_exp_f32_e32 v37, v37
	v_add_f32_e32 v38, 1.0, v38
	v_add_f32_e32 v42, 1.0, v34
	v_add_f32_e32 v39, 1.0, v39
	v_add_f32_e32 v43, 1.0, v35
	v_add_f32_e32 v40, 1.0, v40
	v_add_f32_e32 v44, 1.0, v36
	v_add_f32_e32 v41, 1.0, v41
	v_add_f32_e32 v45, 1.0, v37
	v_rcp_f32_e32 v34, v38
	v_rcp_f32_e32 v42, v42
	v_rcp_f32_e32 v35, v39
	v_rcp_f32_e32 v36, v40
	v_rcp_f32_e32 v37, v41
	v_rcp_f32_e32 v44, v44
	v_rcp_f32_e32 v45, v45
	v_rcp_f32_e32 v43, v43
	v_pk_mul_f32 v[40:41], v[142:143], v[36:37] op_sel_hi:[0,1]
	v_pk_mul_f32 v[38:39], v[142:143], v[34:35] op_sel_hi:[0,1]
	v_pk_mul_f32 v[36:37], v[142:143], v[44:45] op_sel_hi:[0,1]
	v_pk_mul_f32 v[34:35], v[142:143], v[42:43] op_sel_hi:[0,1]
.LBB0_521:
	s_and_b64 vcc, exec, s[42:43]
	v_cvt_pk_bf16_f32 v38, v38, v39
	v_cvt_pk_bf16_f32 v39, v40, v41
	v_cvt_pk_bf16_f32 v40, v34, v35
	v_cvt_pk_bf16_f32 v41, v36, v37
	global_store_dwordx4 v[50:51], v[38:41], off offset:256
	s_cbranch_vccnz .LBB0_523
	s_movk_i32 s12, 0xf000
	s_mov_b32 s13, -1
	v_lshl_add_u64 v[34:35], v[144:145], 0, s[12:13]
	v_cndmask_b32_e64 v39, v35, v147, s[40:41]
	v_cndmask_b32_e64 v38, v34, v146, s[40:41]
	v_mov_b32_e32 v34, v186
	v_mov_b32_e32 v35, v187
	v_mov_b32_e32 v36, v188
	v_mov_b32_e32 v37, v189
	v_mov_b32_e32 v38, v190
	v_mov_b32_e32 v39, v191
	v_mov_b32_e32 v40, v192
	v_mov_b32_e32 v41, v193
	v_add_f32_e32 v30, v30, v34
	v_add_f32_e32 v26, v26, v38
	v_add_f32_e32 v31, v31, v35
	v_add_f32_e32 v27, v27, v39
	v_add_f32_e32 v32, v32, v36
	v_add_f32_e32 v28, v28, v40
	v_add_f32_e32 v33, v33, v37
	v_add_f32_e32 v29, v29, v41
	v_mul_f32_e32 v30, 0xbfb8aa3b, v30
	v_mul_f32_e32 v26, 0xbfb8aa3b, v26
	v_mul_f32_e32 v31, 0xbfb8aa3b, v31
	v_mul_f32_e32 v27, 0xbfb8aa3b, v27
	v_mul_f32_e32 v32, 0xbfb8aa3b, v32
	v_mul_f32_e32 v28, 0xbfb8aa3b, v28
	v_mul_f32_e32 v33, 0xbfb8aa3b, v33
	v_mul_f32_e32 v29, 0xbfb8aa3b, v29
	v_exp_f32_e32 v30, v30
	v_exp_f32_e32 v26, v26
	v_exp_f32_e32 v31, v31
	v_exp_f32_e32 v27, v27
	v_exp_f32_e32 v32, v32
	v_exp_f32_e32 v28, v28
	v_exp_f32_e32 v33, v33
	v_exp_f32_e32 v29, v29
	v_add_f32_e32 v30, 1.0, v30
	v_add_f32_e32 v34, 1.0, v26
	v_add_f32_e32 v31, 1.0, v31
	v_add_f32_e32 v35, 1.0, v27
	v_add_f32_e32 v32, 1.0, v32
	v_add_f32_e32 v36, 1.0, v28
	v_add_f32_e32 v33, 1.0, v33
	v_add_f32_e32 v37, 1.0, v29
	v_rcp_f32_e32 v26, v30
	v_rcp_f32_e32 v34, v34
	v_rcp_f32_e32 v27, v31
	v_rcp_f32_e32 v28, v32
	v_rcp_f32_e32 v29, v33
	v_rcp_f32_e32 v36, v36
	v_rcp_f32_e32 v37, v37
	v_rcp_f32_e32 v35, v35
	v_pk_mul_f32 v[32:33], v[142:143], v[28:29] op_sel_hi:[0,1]
	v_pk_mul_f32 v[30:31], v[142:143], v[26:27] op_sel_hi:[0,1]
	v_pk_mul_f32 v[28:29], v[142:143], v[36:37] op_sel_hi:[0,1]
	v_pk_mul_f32 v[26:27], v[142:143], v[34:35] op_sel_hi:[0,1]
; __device__ __forceinline__ unsigned cvt_pk_bf16(float lo, float hi) { unsigned r; asm volatile("v_cvt_pk_bf16_f32 %0, %1, %2" : "=v"(r) : "v"(lo), "v"(hi)); return r; }
; __device__ __forceinline__ float sigmoidf_(float x) { return __builtin_amdgcn_rcpf(1.0f + __expf(-x)); }
;     __device__ __forceinline__ void operator()(f32x4 (&acc)[2][2][4][2], const Unit& u, int wr, int wc, int fr, int fq) const {
;     ...
;                 bf16_t* rowp = O + (size_t)(row0 + ai * HALF + m * 16) * ldc + col0;
; #pragma unroll
;                 for (int bj = 0; bj < 2; ++bj) {
;                     f32x4 v0 = acc[ai][bj][m][0], v1 = acc[ai][bj][m][1];
;                     f(v0, v1, u.pn, col0 + bj * HALF);
;                     u32x4 w; w.x = cvt_pk_bf16(v0[0], v0[1]); w.y = cvt_pk_bf16(v0[2], v0[3]); w.z = cvt_pk_bf16(v1[0], v1[1]); w.w = cvt_pk_bf16(v1[2], v1[3]);
;                     *(u32x4*)(rowp + bj * HALF) = w;
;                 }
;     __device__ __forceinline__ void operator()(f32x4& a, f32x4& b, int pn, int col) const {
;         if (pn < 8) {
;             const float* pp = (pn < 4) ? (w0 + col) : (a0 + col - 1024);
;             const float sc = (pn < 4) ? -0.6065306597126334f : 1.0f;
;             const f32x4 p0 = *(const f32x4*)pp, p1 = *(const f32x4*)(pp + 4);
; #pragma unroll
;             for (int j = 0; j < 4; ++j) { a[j] = sc * sigmoidf_(a[j] + p0[j]); b[j] = sc * sigmoidf_(b[j] + p1[j]); }
;         }
.LBB0_523:
	v_or_b32_e32 v36, 0xa0, v143
	v_mov_b64_e32 v[34:35], s[34:35]
	v_mad_i64_i32 v[34:35], s[44:45], v36, s78, v[34:35]
	v_lshl_add_u64 v[34:35], v[148:149], 1, v[34:35]
	s_and_b64 vcc, exec, s[42:43]
	v_cvt_pk_bf16_f32 v30, v30, v31
	v_cvt_pk_bf16_f32 v31, v32, v33
	v_cvt_pk_bf16_f32 v32, v26, v27
	v_cvt_pk_bf16_f32 v33, v28, v29
	global_store_dwordx4 v[34:35], v[30:33], off
	s_cbranch_vccnz .LBB0_525
	s_mov_b64 s[12:13], 0x200
	v_lshl_add_u64 v[26:27], v[146:147], 0, s[12:13]
	s_movk_i32 s12, 0xf200
	s_mov_b32 s13, -1
	v_lshl_add_u64 v[28:29], v[144:145], 0, s[12:13]
	v_cndmask_b32_e64 v31, v29, v27, s[40:41]
	v_cndmask_b32_e64 v30, v28, v26, s[40:41]
	v_mov_b32_e32 v26, v194
	v_mov_b32_e32 v27, v195
	v_mov_b32_e32 v28, v196
	v_mov_b32_e32 v29, v197
	v_mov_b32_e32 v30, v198
	v_mov_b32_e32 v31, v199
	v_mov_b32_e32 v32, v200
	v_mov_b32_e32 v33, v201
	v_add_f32_e32 v22, v22, v26
	v_add_f32_e32 v18, v18, v30
	v_add_f32_e32 v23, v23, v27
	v_add_f32_e32 v19, v19, v31
	v_add_f32_e32 v24, v24, v28
	v_add_f32_e32 v20, v20, v32
	v_add_f32_e32 v25, v25, v29
	v_add_f32_e32 v21, v21, v33
	v_mul_f32_e32 v22, 0xbfb8aa3b, v22
	v_mul_f32_e32 v18, 0xbfb8aa3b, v18
	v_mul_f32_e32 v23, 0xbfb8aa3b, v23
	v_mul_f32_e32 v19, 0xbfb8aa3b, v19
	v_mul_f32_e32 v24, 0xbfb8aa3b, v24
	v_mul_f32_e32 v20, 0xbfb8aa3b, v20
	v_mul_f32_e32 v25, 0xbfb8aa3b, v25
	v_mul_f32_e32 v21, 0xbfb8aa3b, v21
	v_exp_f32_e32 v22, v22
	v_exp_f32_e32 v18, v18
	v_exp_f32_e32 v23, v23
	v_exp_f32_e32 v19, v19
	v_exp_f32_e32 v24, v24
	v_exp_f32_e32 v20, v20
	v_exp_f32_e32 v25, v25
	v_exp_f32_e32 v21, v21
	v_add_f32_e32 v22, 1.0, v22
	v_add_f32_e32 v26, 1.0, v18
	v_add_f32_e32 v23, 1.0, v23
	v_add_f32_e32 v27, 1.0, v19
	v_add_f32_e32 v24, 1.0, v24
	v_add_f32_e32 v28, 1.0, v20
	v_add_f32_e32 v25, 1.0, v25
	v_add_f32_e32 v29, 1.0, v21
	v_rcp_f32_e32 v18, v22
	v_rcp_f32_e32 v26, v26
	v_rcp_f32_e32 v19, v23
	v_rcp_f32_e32 v20, v24
	v_rcp_f32_e32 v21, v25
	v_rcp_f32_e32 v28, v28
	v_rcp_f32_e32 v29, v29
	v_rcp_f32_e32 v27, v27
	v_pk_mul_f32 v[24:25], v[142:143], v[20:21] op_sel_hi:[0,1]
	v_pk_mul_f32 v[22:23], v[142:143], v[18:19] op_sel_hi:[0,1]
	v_pk_mul_f32 v[20:21], v[142:143], v[28:29] op_sel_hi:[0,1]
	v_pk_mul_f32 v[18:19], v[142:143], v[26:27] op_sel_hi:[0,1]
.LBB0_525:
	s_and_b64 vcc, exec, s[42:43]
	v_cvt_pk_bf16_f32 v22, v22, v23
	v_cvt_pk_bf16_f32 v23, v24, v25
	v_cvt_pk_bf16_f32 v24, v18, v19
	v_cvt_pk_bf16_f32 v25, v20, v21
	global_store_dwordx4 v[34:35], v[22:25], off offset:256
	s_cbranch_vccnz .LBB0_527
	s_movk_i32 s12, 0xf000
	s_mov_b32 s13, -1
	v_lshl_add_u64 v[18:19], v[144:145], 0, s[12:13]
	v_cndmask_b32_e64 v23, v19, v147, s[40:41]
	v_cndmask_b32_e64 v22, v18, v146, s[40:41]
	v_mov_b32_e32 v18, v186
	v_mov_b32_e32 v19, v187
	v_mov_b32_e32 v20, v188
	v_mov_b32_e32 v21, v189
	v_mov_b32_e32 v22, v190
	v_mov_b32_e32 v23, v191
	v_mov_b32_e32 v24, v192
	v_mov_b32_e32 v25, v193
	v_add_f32_e32 v14, v14, v18
	v_add_f32_e32 v10, v10, v22
	v_add_f32_e32 v15, v15, v19
	v_add_f32_e32 v11, v11, v23
	v_add_f32_e32 v16, v16, v20
	v_add_f32_e32 v12, v12, v24
	v_add_f32_e32 v17, v17, v21
	v_add_f32_e32 v13, v13, v25
	v_mul_f32_e32 v14, 0xbfb8aa3b, v14
	v_mul_f32_e32 v10, 0xbfb8aa3b, v10
	v_mul_f32_e32 v15, 0xbfb8aa3b, v15
	v_mul_f32_e32 v11, 0xbfb8aa3b, v11
	v_mul_f32_e32 v16, 0xbfb8aa3b, v16
	v_mul_f32_e32 v12, 0xbfb8aa3b, v12
	v_mul_f32_e32 v17, 0xbfb8aa3b, v17
	v_mul_f32_e32 v13, 0xbfb8aa3b, v13
	v_exp_f32_e32 v14, v14
	v_exp_f32_e32 v10, v10
	v_exp_f32_e32 v15, v15
	v_exp_f32_e32 v11, v11
	v_exp_f32_e32 v16, v16
	v_exp_f32_e32 v12, v12
	v_exp_f32_e32 v17, v17
	v_exp_f32_e32 v13, v13
	v_add_f32_e32 v14, 1.0, v14
	v_add_f32_e32 v18, 1.0, v10
	v_add_f32_e32 v15, 1.0, v15
	v_add_f32_e32 v19, 1.0, v11
	v_add_f32_e32 v16, 1.0, v16
	v_add_f32_e32 v20, 1.0, v12
	v_add_f32_e32 v17, 1.0, v17
	v_add_f32_e32 v21, 1.0, v13
	v_rcp_f32_e32 v10, v14
	v_rcp_f32_e32 v18, v18
	v_rcp_f32_e32 v11, v15
	v_rcp_f32_e32 v12, v16
	v_rcp_f32_e32 v13, v17
	v_rcp_f32_e32 v20, v20
	v_rcp_f32_e32 v21, v21
	v_rcp_f32_e32 v19, v19
	v_pk_mul_f32 v[16:17], v[142:143], v[12:13] op_sel_hi:[0,1]
	v_pk_mul_f32 v[14:15], v[142:143], v[10:11] op_sel_hi:[0,1]
	v_pk_mul_f32 v[12:13], v[142:143], v[20:21] op_sel_hi:[0,1]
	v_pk_mul_f32 v[10:11], v[142:143], v[18:19] op_sel_hi:[0,1]
.LBB0_527:
	v_or_b32_e32 v20, 0xb0, v143
	v_mov_b64_e32 v[18:19], s[34:35]
	v_mad_i64_i32 v[18:19], s[44:45], v20, s78, v[18:19]
	v_lshl_add_u64 v[18:19], v[148:149], 1, v[18:19]
	s_and_b64 vcc, exec, s[42:43]
	v_cvt_pk_bf16_f32 v14, v14, v15
	v_cvt_pk_bf16_f32 v15, v16, v17
	v_cvt_pk_bf16_f32 v16, v10, v11
	v_cvt_pk_bf16_f32 v17, v12, v13
	global_store_dwordx4 v[18:19], v[14:17], off
	s_cbranch_vccnz .LBB0_529
	s_mov_b64 s[12:13], 0x200
	v_lshl_add_u64 v[10:11], v[146:147], 0, s[12:13]
	s_movk_i32 s12, 0xf200
	s_mov_b32 s13, -1
	v_lshl_add_u64 v[12:13], v[144:145], 0, s[12:13]
	v_cndmask_b32_e64 v15, v13, v11, s[40:41]
	v_cndmask_b32_e64 v14, v12, v10, s[40:41]
	v_mov_b32_e32 v10, v194
	v_mov_b32_e32 v11, v195
	v_mov_b32_e32 v12, v196
	v_mov_b32_e32 v13, v197
	v_mov_b32_e32 v14, v198
	v_mov_b32_e32 v15, v199
	v_mov_b32_e32 v16, v200
	v_mov_b32_e32 v17, v201
	v_add_f32_e32 v6, v6, v10
	v_add_f32_e32 v2, v2, v14
	v_add_f32_e32 v7, v7, v11
	v_add_f32_e32 v3, v3, v15
	v_add_f32_e32 v8, v8, v12
	v_add_f32_e32 v4, v4, v16
	v_add_f32_e32 v9, v9, v13
	v_add_f32_e32 v5, v5, v17
	v_mul_f32_e32 v6, 0xbfb8aa3b, v6
	v_mul_f32_e32 v2, 0xbfb8aa3b, v2
	v_mul_f32_e32 v7, 0xbfb8aa3b, v7
	v_mul_f32_e32 v3, 0xbfb8aa3b, v3
	v_mul_f32_e32 v8, 0xbfb8aa3b, v8
	v_mul_f32_e32 v4, 0xbfb8aa3b, v4
	v_mul_f32_e32 v9, 0xbfb8aa3b, v9
	v_mul_f32_e32 v5, 0xbfb8aa3b, v5
	v_exp_f32_e32 v6, v6
	v_exp_f32_e32 v2, v2
	v_exp_f32_e32 v7, v7
	v_exp_f32_e32 v3, v3
	v_exp_f32_e32 v8, v8
	v_exp_f32_e32 v4, v4
	v_exp_f32_e32 v9, v9
	v_exp_f32_e32 v5, v5
	v_add_f32_e32 v6, 1.0, v6
	v_add_f32_e32 v10, 1.0, v2
	v_add_f32_e32 v7, 1.0, v7
	v_add_f32_e32 v11, 1.0, v3
	v_add_f32_e32 v8, 1.0, v8
	v_add_f32_e32 v12, 1.0, v4
	v_add_f32_e32 v9, 1.0, v9
	v_add_f32_e32 v13, 1.0, v5
	v_rcp_f32_e32 v2, v6
	v_rcp_f32_e32 v10, v10
	v_rcp_f32_e32 v3, v7
	v_rcp_f32_e32 v4, v8
	v_rcp_f32_e32 v5, v9
	v_rcp_f32_e32 v12, v12
	v_rcp_f32_e32 v13, v13
	v_rcp_f32_e32 v11, v11
	v_pk_mul_f32 v[8:9], v[142:143], v[4:5] op_sel_hi:[0,1]
	v_pk_mul_f32 v[6:7], v[142:143], v[2:3] op_sel_hi:[0,1]
	v_pk_mul_f32 v[4:5], v[142:143], v[12:13] op_sel_hi:[0,1]
	v_pk_mul_f32 v[2:3], v[142:143], v[10:11] op_sel_hi:[0,1]
